# seam: wave 0 of every workgroup starts an L2 writeback as soon as its own phase stores are issued (the leader's required writeback then finds little left)
# baseline (speedup 1.0000x reference)
.LBB0_708:
	v_readlane_b32 s6, v253, 8
	s_cmp_eq_u32 s6, 0
	s_cbranch_scc0 .Lseam_nowb
	buffer_wbl2 sc1
